# v075 + GEMM prologues: K-tile 1 loads issued before the first retire wait (vmcnt(2)+barrier moved behind them as vmcnt(8))
# speedup vs baseline: 1.0017x; 1.0017x over previous
.LBB0_227:
	s_add_u32 s60, s12, 0x5400000
	s_addc_u32 s61, s13, 0
	s_add_u32 s62, s12, 0x100000
	s_addc_u32 s63, s13, 0
	s_add_u32 s64, s12, 0x200000
	s_addc_u32 s65, s13, 0
	s_and_b32 s21, s10, 3
	s_add_i32 m0, s35, 0x18000
	v_lshl_add_u64 v[10:11], v[10:11], 0, s[30:31]
	s_lshl_b32 s12, s24, 13
	s_lshl_b32 s13, s21, 12
	global_load_lds_dwordx4 v[10:11], off
	v_lshl_add_u64 v[8:9], v[8:9], 0, s[30:31]
	s_add_i32 m0, s35, 0x1a000
	s_add_i32 s82, s35, 0x8000
	s_add_i32 s27, s35, 0xa000
	global_load_lds_dwordx4 v[8:9], off
	v_lshl_add_u64 v[4:5], v[4:5], 0, s[30:31]
	s_mov_b32 m0, s82
	s_add_u32 s10, s76, 0x40080
	global_load_lds_dwordx4 v[4:5], off
	v_lshl_add_u64 v[4:5], v[6:7], 0, s[30:31]
	s_mov_b32 m0, s27
	s_addc_u32 s11, s77, 0
	global_load_lds_dwordx4 v[4:5], off
	s_add_i32 m0, s35, 0x1c000
	v_lshl_add_u64 v[4:5], s[10:11], 0, v[2:3]
	global_load_lds_dwordx4 v[4:5], off
	v_lshl_add_u64 v[4:5], s[10:11], 0, v[152:153]
	s_add_i32 m0, s35, 0x1e000
	s_cmpk_lt_u32 s6, 0x100
	global_load_lds_dwordx4 v[4:5], off
	s_waitcnt vmcnt(8)
	s_barrier
	v_bfe_u32 v5, v12, 4, 2
	v_and_b32_e32 v4, 15, v12
	v_lshlrev_b32_e32 v7, 4, v5
	v_readlane_b32 s6, v255, 10
	v_lshl_or_b32 v166, s24, 6, v4
	v_lshl_or_b32 v7, v4, 6, v7
	v_lshlrev_b32_e32 v4, 2, v4
	s_cselect_b64 s[66:67], -1, 0
	v_cmp_eq_u32_e64 s[98:99], 3, v205
	s_nop 3
	s_and_saveexec_b64 s[100:101], s[98:99]
	v_mov_b32_e32 v206, v201
	v_mov_b32_e32 v207, v202
	v_mov_b32_e32 v201, v203
	v_pk_add_f32 v[200:201], v[206:207], v[200:201]
	s_nop 0
	v_add_f32_e32 v200, v200, v201
	v_fmamk_f32 v200, v200, 0x3a800000, v193
	v_rsq_f32_e32 v200, v200
	s_or_b64 exec, exec, s[100:101]
	v_cmp_eq_u32_e64 s[98:99], 2, v205
	s_nop 3
	s_and_saveexec_b64 s[100:101], s[98:99]
	v_mul_f32_e32 v200, 0x3e38aa3b, v200
	s_or_b64 exec, exec, s[100:101]
	v_cmp_ne_u32_e64 s[98:99], 0, v205
	s_nop 3
	s_and_saveexec_b64 s[100:101], s[98:99]
	ds_write_b32 v194, v200
	s_or_b64 exec, exec, s[100:101]
	v_lshl_add_u32 v203, v5, 5, s6
	s_lshl_b32 s6, s24, 8
	v_and_b32_e32 v8, 32, v4
	s_add_i32 s6, s6, 0
	v_bitop3_b32 v9, v7, s12, v8 bitop3:0xde
	s_add_i32 s12, s6, 0x20000
	s_add_i32 s6, s6, 0x20200
	v_add_u32_e32 v204, s12, v4
	v_add_u32_e32 v205, s6, v4
	v_lshlrev_b32_e32 v4, 14, v13
	v_and_b32_e32 v4, 0xffff8000, v4
	v_lshlrev_b32_e32 v6, 3, v5
	v_cmp_eq_u32_e64 s[10:11], 0, v5
	v_lshl_add_u32 v4, v14, 11, v4
	v_and_b32_e32 v5, 1, v13
	v_lshl_or_b32 v4, v5, 6, v4
	v_lshl_add_u32 v154, v15, 1, v4
	v_lshlrev_b32_e32 v4, 14, v16
	v_and_b32_e32 v4, 0xffff8000, v4
	s_waitcnt vmcnt(6)
	v_lshl_add_u32 v4, v17, 11, v4
	v_and_b32_e32 v5, 1, v16
	v_lshl_or_b32 v4, v5, 6, v4
	v_bitop3_b32 v184, v7, s13, v8 bitop3:0xde
	v_lshl_or_b32 v185, s21, 6, v6
	s_mov_b32 s80, 0
	v_or_b32_e32 v186, 16, v166
	v_or_b32_e32 v187, 32, v166
	v_or_b32_e32 v188, 48, v166
	v_add_u32_e32 v189, 0x80, v166
	v_add_u32_e32 v200, 0x90, v166
	v_add_u32_e32 v201, 0xa0, v166
	v_add_u32_e32 v202, 0xb0, v166
	s_ashr_i32 s89, s8, 31
	v_mov_b32_e32 v155, v3
	v_lshl_add_u32 v156, v18, 1, v4
	v_mov_b32_e32 v157, v3
	v_add_u32_e32 v206, 0, v9
	s_barrier
	s_branch .LBB0_230

.LBB0_595:
	v_lshl_add_u64 v[158:159], s[70:71], 0, v[2:3]
	v_mov_b32_e32 v137, v3
	v_lshlrev_b32_e32 v145, 6, v153
	v_and_b32_e32 v156, 48, v154
	s_movk_i32 s6, 0x3c0
	v_lshlrev_b32_e32 v157, 2, v153
	v_lshl_add_u64 v[160:161], s[70:71], 0, v[136:137]
	v_mov_b32_e32 v133, v3
	v_and_or_b32 v145, v145, s6, v156
	s_lshl_b32 s6, s10, 13
	v_and_b32_e32 v157, 32, v157
	s_add_i32 m0, s3, 0x18000
	v_lshl_add_u64 v[158:159], v[158:159], 0, s[30:31]
	v_lshl_add_u64 v[162:163], s[64:65], 0, v[132:133]
	v_mov_b32_e32 v135, v3
	v_bitop3_b32 v145, v145, s6, v157 bitop3:0xde
	s_lshl_b32 s6, s5, 12
	global_load_lds_dwordx4 v[158:159], off
	v_lshl_add_u64 v[158:159], v[160:161], 0, s[30:31]
	s_add_i32 m0, s3, 0x1a000
	s_add_i32 s10, s3, 0x8000
	s_add_i32 s11, s3, 0xa000
	v_lshl_add_u64 v[164:165], s[64:65], 0, v[134:135]
	global_load_lds_dwordx4 v[158:159], off
	v_lshl_add_u64 v[158:159], v[162:163], 0, s[30:31]
	s_mov_b32 m0, s10
	s_add_u32 s12, s70, 0x40080
	global_load_lds_dwordx4 v[158:159], off
	v_lshl_add_u64 v[158:159], v[164:165], 0, s[30:31]
	s_mov_b32 m0, s11
	s_addc_u32 s13, s71, 0
	global_load_lds_dwordx4 v[158:159], off
	s_add_i32 m0, s3, 0x1c000
	v_lshl_add_u64 v[158:159], s[12:13], 0, v[2:3]
	global_load_lds_dwordx4 v[158:159], off
	v_lshl_add_u64 v[158:159], s[12:13], 0, v[136:137]
	s_add_i32 m0, s3, 0x1e000
	v_lshl_or_b32 v156, v138, 6, v156
	global_load_lds_dwordx4 v[158:159], off
	s_waitcnt vmcnt(8)
	s_barrier
	v_lshlrev_b32_e32 v138, 2, v138
	v_and_b32_e32 v138, 32, v138
	v_bitop3_b32 v156, v156, s6, v138 bitop3:0xde
	v_lshlrev_b32_e32 v138, 14, v139
	v_and_b32_e32 v138, 0xffff8000, v138
	v_lshl_add_u32 v138, v140, 11, v138
	v_and_b32_e32 v139, 1, v139
	v_lshlrev_b32_e32 v140, 14, v142
	v_lshl_or_b32 v138, v139, 6, v138
	v_and_b32_e32 v140, 0xffff8000, v140
	s_waitcnt vmcnt(6)
	v_lshl_add_u32 v138, v141, 1, v138
	v_lshl_add_u32 v140, v143, 11, v140
	v_and_b32_e32 v141, 1, v142
	v_lshl_or_b32 v140, v141, 6, v140
	v_or_b32_e32 v157, s20, v155
	v_mov_b32_e32 v139, v3
	v_lshl_add_u32 v140, v144, 1, v140
	v_mov_b32_e32 v141, v3
	s_mov_b32 s59, 0
	v_add_u32_e32 v158, 0, v145
	s_barrier
	s_branch .LBB0_597

.LBB0_658:
	s_add_u32 s57, s16, 0x5400000
	v_and_b32_e32 v18, 15, v17
	v_lshrrev_b32_e32 v17, 1, v17
	s_addc_u32 s74, s17, 0
	v_and_b32_e32 v17, 24, v17
	s_add_u32 s16, s16, 0x100000
	v_lshlrev_b32_e32 v19, 1, v17
	s_addc_u32 s17, s17, 0
	v_lshl_or_b32 v141, s10, 6, v18
	v_lshl_or_b32 v19, v18, 6, v19
	v_lshlrev_b32_e32 v18, 2, v18
	s_lshl_b32 s11, s11, 5
	s_lshl_b32 s12, s10, 13
	v_and_b32_e32 v20, 32, v18
	s_and_b32 s75, s11, 0x60
	s_add_i32 m0, s35, 0x18000
	v_lshl_add_u64 v[10:11], v[10:11], 0, s[30:31]
	v_bitop3_b32 v21, v19, s12, v20 bitop3:0xde
	s_lshl_b32 s12, s75, 7
	global_load_lds_dwordx4 v[10:11], off
	v_lshl_add_u64 v[8:9], v[8:9], 0, s[30:31]
	s_add_i32 m0, s35, 0x1a000
	s_add_i32 s76, s35, 0x8000
	s_add_i32 s77, s35, 0xa000
	v_bitop3_b32 v148, v19, s12, v20 bitop3:0xde
	global_load_lds_dwordx4 v[8:9], off
	v_lshl_add_u64 v[4:5], v[4:5], 0, s[30:31]
	s_mov_b32 m0, s76
	s_add_u32 s12, s70, 0x40080
	global_load_lds_dwordx4 v[4:5], off
	v_lshl_add_u64 v[4:5], v[6:7], 0, s[30:31]
	s_mov_b32 m0, s77
	s_addc_u32 s13, s71, 0
	global_load_lds_dwordx4 v[4:5], off
	s_add_i32 m0, s35, 0x1c000
	v_lshl_add_u64 v[4:5], s[12:13], 0, v[134:135]
	global_load_lds_dwordx4 v[4:5], off
	v_lshl_add_u64 v[4:5], s[12:13], 0, v[138:139]
	s_add_i32 m0, s35, 0x1e000
	s_cmpk_lt_u32 s6, 0x100
	global_load_lds_dwordx4 v[4:5], off
	s_waitcnt vmcnt(8)
	s_barrier
	v_lshlrev_b32_e32 v4, 14, v2
	v_and_b32_e32 v4, 0xffff8000, v4
	v_lshl_add_u32 v4, v12, 11, v4
	v_and_b32_e32 v2, 1, v2
	v_lshl_or_b32 v2, v2, 6, v4
	v_lshl_add_u32 v142, v13, 1, v2
	v_lshlrev_b32_e32 v2, 14, v14
	s_cselect_b64 s[18:19], -1, 0
	v_readlane_b32 s64, v255, 6
	v_readlane_b32 s65, v255, 7
	s_nop 3
	s_and_saveexec_b64 s[72:73], s[64:65]
	v_mov_b32_e32 v206, v201
	v_mov_b32_e32 v207, v202
	v_mov_b32_e32 v201, v203
	v_pk_add_f32 v[200:201], v[206:207], v[200:201]
	s_nop 0
	v_add_f32_e32 v200, v200, v201
	v_fmamk_f32 v200, v200, 0x3a800000, v193
	v_rsq_f32_e32 v200, v200
	s_nop 0
	ds_write_b32 v194, v200
	s_or_b64 exec, exec, s[72:73]
	s_lshl_b32 s6, s10, 8
	v_and_b32_e32 v2, 0xffff8000, v2
	s_waitcnt vmcnt(6)
	s_add_i32 s6, s6, 0
	v_lshl_add_u32 v2, v15, 11, v2
	v_and_b32_e32 v4, 1, v14
	s_add_i32 s10, s6, 0x20000
	s_add_i32 s6, s6, 0x20200
	v_lshl_or_b32 v2, v4, 6, v2
	v_and_or_b32 v140, s11, 32, v17
	s_ashr_i32 s78, s4, 31
	v_add_u32_e32 v149, s10, v18
	v_add_u32_e32 v150, s6, v18
	v_mov_b32_e32 v143, v3
	v_lshl_add_u32 v144, v16, 1, v2
	v_mov_b32_e32 v145, v3
	s_mov_b32 s79, 0
	v_add_u32_e32 v151, 0, v21
	s_barrier
	s_branch .LBB0_661

.LBB0_825:
	v_lshlrev_b32_e32 v145, 6, v154
	v_and_b32_e32 v156, 48, v153
	s_movk_i32 s6, 0x3c0
	v_lshlrev_b32_e32 v157, 2, v154
	v_and_or_b32 v145, v145, s6, v156
	s_lshl_b32 s6, s10, 13
	v_and_b32_e32 v157, 32, v157
	v_bitop3_b32 v145, v145, s6, v157 bitop3:0xde
	s_lshl_b32 s6, s5, 12
	s_add_u32 s10, s66, 0x20000
	s_addc_u32 s11, s67, 0
	s_add_i32 m0, s24, 0x18000
	v_lshl_add_u64 v[158:159], s[10:11], 0, v[2:3]
	global_load_lds_dwordx4 v[158:159], off
	s_add_i32 m0, s24, 0x1a000
	v_mov_b32_e32 v137, v3
	s_add_u32 s12, s68, 0x200000
	v_mov_b32_e32 v133, v3
	v_lshl_add_u64 v[158:159], s[10:11], 0, v[136:137]
	s_addc_u32 s13, s69, 0
	s_add_i32 s10, s24, 0x8000
	v_mov_b32_e32 v135, v3
	global_load_lds_dwordx4 v[158:159], off
	v_lshl_add_u64 v[158:159], s[12:13], 0, v[132:133]
	s_mov_b32 m0, s10
	s_add_i32 s11, s24, 0xa000
	global_load_lds_dwordx4 v[158:159], off
	v_lshl_add_u64 v[158:159], s[12:13], 0, v[134:135]
	s_add_u32 s12, s66, 0x24000
	s_mov_b32 m0, s11
	s_addc_u32 s13, s67, 0
	global_load_lds_dwordx4 v[158:159], off
	s_add_i32 m0, s24, 0x1c000
	v_lshl_add_u64 v[158:159], s[12:13], 0, v[2:3]
	global_load_lds_dwordx4 v[158:159], off
	v_lshl_add_u64 v[158:159], s[12:13], 0, v[136:137]
	s_add_i32 m0, s24, 0x1e000
	v_lshl_or_b32 v156, v138, 6, v156
	global_load_lds_dwordx4 v[158:159], off
	s_waitcnt vmcnt(8)
	s_barrier
	v_lshlrev_b32_e32 v138, 2, v138
	v_and_b32_e32 v138, 32, v138
	v_bitop3_b32 v156, v156, s6, v138 bitop3:0xde
	v_lshlrev_b32_e32 v138, 10, v139
	v_and_b32_e32 v138, 0xfffff800, v138
	v_lshl_add_u32 v138, v140, 7, v138
	v_and_b32_e32 v139, 1, v139
	v_lshlrev_b32_e32 v140, 10, v142
	v_lshl_or_b32 v138, v139, 6, v138
	v_and_b32_e32 v140, 0xfffff800, v140
	v_lshl_add_u32 v138, v141, 1, v138
	v_lshl_add_u32 v140, v143, 7, v140
	v_and_b32_e32 v141, 1, v142
	s_waitcnt vmcnt(6)
	v_lshl_or_b32 v140, v141, 6, v140
	v_mov_b32_e32 v139, v3
	s_mov_b64 s[12:13], 0x204000
	v_lshl_add_u32 v140, v144, 1, v140
	v_mov_b32_e32 v141, v3
	v_or_b32_e32 v157, s9, v155
	v_lshl_add_u64 v[138:139], v[138:139], 0, s[12:13]
	v_lshl_add_u64 v[140:141], v[140:141], 0, s[12:13]
	s_mov_b32 s61, 0
	v_add_u32_e32 v158, 0, v145
	s_barrier
	s_branch .LBB0_827
